# gemm_phase prologues: all seven staging groups issued before the first wait (one exposed latency per GEMM phase instead of two)
# speedup vs baseline: 1.0023x; 1.0023x over previous
; #define PG8_STAGE(bufoff, gbase, voff) do { _Pragma("unroll") for (int _i = 0; _i < 2; ++_i) { const char* _gb = (const char*)(gbase) + (size_t)_i * (voff##_q); asm volatile("" : "+s"(_gb)); \
;         __builtin_amdgcn_global_load_lds((const unsigned*)(_gb + (voff)), (LAS unsigned*)(lds + (bufoff) + ldsw + _i * 8192), 16, 0, 0); } } while (0)
; #define PG8_WAIT_V(n) asm volatile("s_waitcnt vmcnt(" #n ")" ::: "memory")
; #define PG8_BAR __builtin_amdgcn_s_barrier()
; template <class Epi, class Sched>
; __device__ __forceinline__ void gemm_phase(int wv, LAS unsigned char* lds, const Gemm g, const Sched& S, const Epi& E) { LIDS
;     ...
;     PG8_STAGE(PG8_SB(0, 0), cB, voffB); PG8_STAGE(PG8_SA(0, 0), cA, voffA); PG8_STAGE(PG8_SB(0, 1), cB + hstepB, voffB); PG8_STAGE(PG8_SA(0, 1), cA + hstepA, voffA);
;     if (wr == 1) PG8_BAR;
;     PG8_WAIT_V(4); PG8_BAR;
;     PG8_STAGE(PG8_SB(1, 0), cB + kstepB, voffB); PG8_STAGE(PG8_SA(1, 0), cA + kstepA, voffA); PG8_STAGE(PG8_SB(1, 1), cB + hstepB + kstepB, voffB);
;     PG8_WAIT_V(6); PG8_BAR;
.LBB0_23:
	s_lshl_b32 s4, s4, 5
	s_and_b32 s26, s4, 0x60
	s_lshl_b32 s25, s5, 6
	s_lshl_b32 s6, s5, 13
	s_lshl_b32 s7, s26, 7
	s_add_u32 s4, s78, 0x80
	s_addc_u32 s5, s79, 0
	s_add_i32 m0, s21, 0x18000
	v_mov_b32_e32 v129, v177
	v_lshl_add_u64 v[2:3], s[4:5], 0, v[176:177]
	s_add_u32 s4, s78, 0x40080
	s_addc_u32 s5, s79, 0
	global_load_lds_dwordx4 v[2:3], off
	s_add_i32 m0, s21, 0x1a000
	v_lshl_add_u64 v[2:3], s[4:5], 0, v[176:177]
	s_add_u32 s4, s72, 0x80
	s_addc_u32 s5, s73, 0
	global_load_lds_dwordx4 v[2:3], off
	s_add_i32 s27, s21, 0x8000
	v_lshl_add_u64 v[2:3], s[4:5], 0, v[128:129]
	s_add_u32 s4, s72, 0x40080
	s_mov_b32 m0, s27
	s_addc_u32 s5, s73, 0
	global_load_lds_dwordx4 v[2:3], off
	s_add_i32 s28, s21, 0xa000
	v_lshl_add_u64 v[2:3], s[4:5], 0, v[128:129]
	s_add_u32 s4, s78, 0x80080
	s_mov_b32 m0, s28
	s_addc_u32 s5, s79, 0
	global_load_lds_dwordx4 v[2:3], off
	s_add_i32 m0, s21, 0x1c000
	v_and_b32_e32 v1, 48, v0
	v_lshl_add_u64 v[2:3], s[4:5], 0, v[176:177]
	s_add_u32 s4, s78, 0xc0080
	s_addc_u32 s5, s79, 0
	global_load_lds_dwordx4 v[2:3], off
	s_add_i32 m0, s21, 0x1e000
	v_lshl_add_u64 v[2:3], s[4:5], 0, v[176:177]
	global_load_lds_dwordx4 v[2:3], off
	v_lshlrev_b32_e32 v2, 6, v0
	v_lshlrev_b32_e32 v0, 2, v0
	v_and_or_b32 v1, v2, s74, v1
	v_and_b32_e32 v0, 32, v0
	s_waitcnt vmcnt(10)
	s_barrier
	s_waitcnt vmcnt(6)
	v_bitop3_b32 v2, v1, s6, v0 bitop3:0xde
	s_sext_i32_i8 s30, s0
	v_bitop3_b32 v131, s7, v1, v0 bitop3:0xf6
	s_ashr_i32 s0, s17, 31
	s_mov_b32 s29, 0
	v_add_u32_e32 v132, 16, v2
	s_barrier

; #define PG8_STAGE(bufoff, gbase, voff) do { _Pragma("unroll") for (int _i = 0; _i < 2; ++_i) { const char* _gb = (const char*)(gbase) + (size_t)_i * (voff##_q); asm volatile("" : "+s"(_gb)); \
;         __builtin_amdgcn_global_load_lds((const unsigned*)(_gb + (voff)), (LAS unsigned*)(lds + (bufoff) + ldsw + _i * 8192), 16, 0, 0); } } while (0)
; #define PG8_WAIT_V(n) asm volatile("s_waitcnt vmcnt(" #n ")" ::: "memory")
; #define PG8_BAR __builtin_amdgcn_s_barrier()
; template <class Epi, class Sched>
; __device__ __forceinline__ void gemm_phase(int wv, LAS unsigned char* lds, const Gemm g, const Sched& S, const Epi& E) { LIDS
;     ...
;     PG8_STAGE(PG8_SB(0, 0), cB, voffB); PG8_STAGE(PG8_SA(0, 0), cA, voffA); PG8_STAGE(PG8_SB(0, 1), cB + hstepB, voffB); PG8_STAGE(PG8_SA(0, 1), cA + hstepA, voffA);
;     if (wr == 1) PG8_BAR;
;     PG8_WAIT_V(4); PG8_BAR;
;     PG8_STAGE(PG8_SB(1, 0), cB + kstepB, voffB); PG8_STAGE(PG8_SA(1, 0), cA + kstepA, voffA); PG8_STAGE(PG8_SB(1, 1), cB + hstepB + kstepB, voffB);
;     PG8_WAIT_V(6); PG8_BAR;
; PHASE_FN void ph_glu(int wv, const Params& p, int layer, LAS unsigned char* lds) { LIDS
;     Gemm g{WSP(bf16_t, OFF_YACT), WSP(bf16_t, OFF_WGLU), 1024, 1024, 1024, (size_t)BM * 32, (size_t)BM * 1024 * 2, 1};
;     StaticOrder S; S.init(SEQ, 2048, gdim_l, bid_l); EpiGlu E{WSP(bf16_t, OFF_MIXED), WSP(bf16_t, OFF_PROJ)}; gemm_phase(wv, lds, g, S, E);
.LBB0_46:
	s_lshl_b32 s4, s4, 5
	s_and_b32 s94, s4, 0x60
	s_lshl_b32 s91, s5, 6
	s_lshl_b32 s6, s5, 13
	s_lshl_b32 s7, s94, 7
	s_add_u32 s4, s78, 0x80
	s_addc_u32 s5, s79, 0
	s_add_i32 m0, s69, 0x18000
	v_mov_b32_e32 v161, v177
	v_lshl_add_u64 v[2:3], s[4:5], 0, v[176:177]
	s_add_u32 s4, s78, 0x20080
	s_addc_u32 s5, s79, 0
	global_load_lds_dwordx4 v[2:3], off
	s_add_i32 m0, s69, 0x1a000
	v_lshl_add_u64 v[2:3], s[4:5], 0, v[176:177]
	s_add_u32 s4, s72, 0x200000
	s_addc_u32 s5, s73, 0
	global_load_lds_dwordx4 v[2:3], off
	s_add_i32 s95, s69, 0x8000
	v_lshl_add_u64 v[2:3], s[4:5], 0, v[160:161]
	s_add_u32 s4, s72, 0x200800
	s_mov_b32 m0, s95
	s_addc_u32 s5, s73, 0
	global_load_lds_dwordx4 v[2:3], off
	s_add_i32 s57, s69, 0xa000
	v_lshl_add_u64 v[2:3], s[4:5], 0, v[160:161]
	s_add_u32 s4, s78, 0x40080
	s_mov_b32 m0, s57
	s_addc_u32 s5, s79, 0
	global_load_lds_dwordx4 v[2:3], off
	s_add_i32 m0, s69, 0x1c000
	v_and_b32_e32 v1, 48, v0
	v_lshl_add_u64 v[2:3], s[4:5], 0, v[176:177]
	s_add_u32 s4, s78, 0x60080
	s_addc_u32 s5, s79, 0
	global_load_lds_dwordx4 v[2:3], off
	s_add_i32 m0, s69, 0x1e000
	v_lshl_add_u64 v[2:3], s[4:5], 0, v[176:177]
	global_load_lds_dwordx4 v[2:3], off
	v_lshlrev_b32_e32 v2, 6, v0
	v_lshlrev_b32_e32 v0, 2, v0
	v_and_or_b32 v1, v2, s74, v1
	v_and_b32_e32 v0, 32, v0
	s_waitcnt vmcnt(10)
	s_barrier
	s_waitcnt vmcnt(6)
	v_bitop3_b32 v2, v1, s6, v0 bitop3:0xde
	s_sext_i32_i8 s16, s0
	v_bitop3_b32 v173, s7, v1, v0 bitop3:0xf6
	s_ashr_i32 s0, s56, 31
	s_mov_b32 s58, 0
	v_add_u32_e32 v174, 16, v2
	s_barrier

; #define PG8_STAGE(bufoff, gbase, voff) do { _Pragma("unroll") for (int _i = 0; _i < 2; ++_i) { const char* _gb = (const char*)(gbase) + (size_t)_i * (voff##_q); asm volatile("" : "+s"(_gb)); \
;         __builtin_amdgcn_global_load_lds((const unsigned*)(_gb + (voff)), (LAS unsigned*)(lds + (bufoff) + ldsw + _i * 8192), 16, 0, 0); } } while (0)
; #define PG8_WAIT_V(n) asm volatile("s_waitcnt vmcnt(" #n ")" ::: "memory")
; #define PG8_BAR __builtin_amdgcn_s_barrier()
; template <class Epi, class Sched>
; __device__ __forceinline__ void gemm_phase(int wv, LAS unsigned char* lds, const Gemm g, const Sched& S, const Epi& E) { LIDS
;     ...
;     PG8_STAGE(PG8_SB(0, 0), cB, voffB); PG8_STAGE(PG8_SA(0, 0), cA, voffA); PG8_STAGE(PG8_SB(0, 1), cB + hstepB, voffB); PG8_STAGE(PG8_SA(0, 1), cA + hstepA, voffA);
;     if (wr == 1) PG8_BAR;
;     PG8_WAIT_V(4); PG8_BAR;
;     PG8_STAGE(PG8_SB(1, 0), cB + kstepB, voffB); PG8_STAGE(PG8_SA(1, 0), cA + kstepA, voffA); PG8_STAGE(PG8_SB(1, 1), cB + hstepB + kstepB, voffB);
;     PG8_WAIT_V(6); PG8_BAR;
; PHASE_FN void ph_y(int wv, const Params& p, int layer, LAS unsigned char* lds) { LIDS
;     Gemm g{WSP(bf16_t, OFF_UCAT), WSP(bf16_t, OFF_BT2 + layer * BT2_BYTES), KCAT, KCAT, KCAT, (size_t)BM * KCAT * 2, (size_t)BM * KCAT * 2, 0};
;     GroupOrder S{gdim_l, bid_l}; EpiY E{WSP(bf16_t, OFF_YACT), WSP(bf16_t, OFF_UCAT), p.d_skip + (size_t)layer * 1024}; gemm_phase(wv, lds, g, S, E);
.LBB0_66:
	s_mov_b32 s6, s12
	v_writelane_b32 v254, s6, 56
	v_and_b32_e32 v5, 48, v4
	v_lshlrev_b32_e32 v6, 6, v4
	v_writelane_b32 v254, s7, 57
	s_lshl_b64 s[6:7], s[12:13], 12
	s_add_u32 s6, s50, s6
	v_writelane_b32 v255, s6, 1
	s_addc_u32 s6, s51, s7
	s_lshl_b32 s4, s4, 5
	v_lshlrev_b32_e32 v4, 2, v4
	s_and_b32 s4, s4, 0x60
	v_writelane_b32 v255, s6, 2
	s_lshl_b32 s6, s5, 6
	s_lshl_b32 s5, s5, 13
	v_and_or_b32 v5, v6, s74, v5
	v_and_b32_e32 v4, 32, v4
	s_mov_b32 s80, s4
	s_lshl_b32 s4, s4, 7
	v_bitop3_b32 v217, s4, v5, v4 bitop3:0xf6
	s_add_u32 s4, s72, 0x80
	v_bitop3_b32 v6, v5, s5, v4 bitop3:0xde
	s_addc_u32 s5, s73, 0
	s_add_i32 m0, s94, 0x18000
	v_mov_b32_e32 v165, v177
	v_lshl_add_u64 v[4:5], s[4:5], 0, v[176:177]
	s_add_u32 s4, s72, 0xc080
	s_addc_u32 s5, s73, 0
	global_load_lds_dwordx4 v[4:5], off
	s_add_i32 m0, s94, 0x1a000
	v_lshl_add_u64 v[4:5], s[4:5], 0, v[176:177]
	s_add_u32 s4, s78, 0x80
	s_addc_u32 s5, s79, 0
	global_load_lds_dwordx4 v[4:5], off
	v_writelane_b32 v255, s6, 3
	v_lshl_add_u64 v[4:5], s[4:5], 0, v[164:165]
	s_add_i32 s4, s94, 0x8000
	s_add_u32 s6, s78, 0xc080
	s_mov_b32 m0, s4
	s_addc_u32 s7, s79, 0
	global_load_lds_dwordx4 v[4:5], off
	s_add_i32 s5, s94, 0xa000
	v_lshl_add_u64 v[4:5], s[6:7], 0, v[164:165]
	s_add_u32 s6, s72, 0x18080
	s_mov_b32 m0, s5
	s_addc_u32 s7, s73, 0
	global_load_lds_dwordx4 v[4:5], off
	s_add_i32 m0, s94, 0x1c000
	v_mov_b32_e32 v1, v0
	v_lshl_add_u64 v[4:5], s[6:7], 0, v[176:177]
	s_add_u32 s6, s72, 0x24080
	s_addc_u32 s7, s73, 0
	global_load_lds_dwordx4 v[4:5], off
	s_add_i32 m0, s94, 0x1e000
	v_lshl_add_u64 v[4:5], s[6:7], 0, v[176:177]
	global_load_lds_dwordx4 v[4:5], off
	s_lshl_b32 s6, s0, 3
	s_and_b32 s6, s6, 56
	s_ashr_i32 s7, s0, 5
	s_add_i32 s6, s6, s7
	s_waitcnt vmcnt(10)
	s_barrier
	s_waitcnt vmcnt(6)
	s_lshl_b32 s6, s6, 2
	s_bfe_u32 s7, s0, 0x20003
	s_or_b32 s6, s6, s7
	v_mov_b32_e32 v2, v0
	v_mov_b32_e32 v3, v0
	v_add_u32_e32 v218, 16, v6
	v_writelane_b32 v255, s6, 4
	s_mov_b64 s[8:9], s[78:79]
	s_mov_b32 s81, s10
	s_barrier
	s_branch .LBB0_68

; #define PG8_STAGE(bufoff, gbase, voff) do { _Pragma("unroll") for (int _i = 0; _i < 2; ++_i) { const char* _gb = (const char*)(gbase) + (size_t)_i * (voff##_q); asm volatile("" : "+s"(_gb)); \
;         __builtin_amdgcn_global_load_lds((const unsigned*)(_gb + (voff)), (LAS unsigned*)(lds + (bufoff) + ldsw + _i * 8192), 16, 0, 0); } } while (0)
; #define PG8_WAIT_V(n) asm volatile("s_waitcnt vmcnt(" #n ")" ::: "memory")
; #define PG8_BAR __builtin_amdgcn_s_barrier()
; template <class Epi, class Sched>
; __device__ __forceinline__ void gemm_phase(int wv, LAS unsigned char* lds, const Gemm g, const Sched& S, const Epi& E) { LIDS
;     ...
;     PG8_STAGE(PG8_SB(0, 0), cB, voffB); PG8_STAGE(PG8_SA(0, 0), cA, voffA); PG8_STAGE(PG8_SB(0, 1), cB + hstepB, voffB); PG8_STAGE(PG8_SA(0, 1), cA + hstepA, voffA);
;     if (wr == 1) PG8_BAR;
;     PG8_WAIT_V(4); PG8_BAR;
;     PG8_STAGE(PG8_SB(1, 0), cB + kstepB, voffB); PG8_STAGE(PG8_SA(1, 0), cA + kstepA, voffA); PG8_STAGE(PG8_SB(1, 1), cB + hstepB + kstepB, voffB);
;     PG8_WAIT_V(6); PG8_BAR;
; PHASE_FN void ph_q(int wv, const Params& p, int layer, LAS unsigned char* lds) { LIDS
;     Gemm g{WSP(bf16_t, OFF_PROJ) + C_CQ, WSP(bf16_t, OFF_WUQ), NIN, 512, 512, (size_t)BM * NIN * 2, (size_t)BM * 512 * 2, 0};
;     StaticOrder S; S.init(SEQ, NQ, gdim_l, bid_l); EpiQ E{WSP(bf16_t, OFF_Q), WSP(float, OFF_SS), WSP(float, OFF_COS), WSP(float, OFF_SIN)}; gemm_phase(wv, lds, g, S, E);
.LBB0_118:
	s_lshl_b32 s4, s4, 5
	s_and_b32 s53, s4, 0x60
	s_lshl_b32 s52, s5, 6
	s_lshl_b32 s7, s5, 13
	s_lshl_b32 s9, s53, 7
	s_add_u32 s4, s78, 0x80
	s_addc_u32 s5, s79, 0
	v_mov_b32_e32 v139, v177
	s_add_i32 m0, s91, 0x18000
	v_mov_b32_e32 v137, v177
	v_lshl_add_u64 v[2:3], s[4:5], 0, v[138:139]
	s_add_u32 s4, s78, 0x10080
	s_addc_u32 s5, s79, 0
	global_load_lds_dwordx4 v[2:3], off
	s_add_i32 m0, s91, 0x1a000
	v_lshl_add_u64 v[2:3], s[4:5], 0, v[138:139]
	s_add_u32 s4, s68, 0x80
	s_addc_u32 s5, s69, 0
	global_load_lds_dwordx4 v[2:3], off
	s_add_i32 s55, s91, 0x8000
	v_lshl_add_u64 v[2:3], s[4:5], 0, v[136:137]
	s_add_u32 s4, s68, 0x80080
	s_mov_b32 m0, s55
	s_addc_u32 s5, s69, 0
	global_load_lds_dwordx4 v[2:3], off
	s_add_i32 s57, s91, 0xa000
	v_lshl_add_u64 v[2:3], s[4:5], 0, v[136:137]
	s_add_u32 s4, s78, 0x20080
	s_mov_b32 m0, s57
	s_addc_u32 s5, s79, 0
	global_load_lds_dwordx4 v[2:3], off
	s_add_i32 m0, s91, 0x1c000
	v_and_b32_e32 v1, 48, v0
	v_lshl_add_u64 v[2:3], s[4:5], 0, v[138:139]
	s_add_u32 s4, s78, 0x30080
	s_addc_u32 s5, s79, 0
	global_load_lds_dwordx4 v[2:3], off
	s_add_i32 m0, s91, 0x1e000
	v_lshl_add_u64 v[2:3], s[4:5], 0, v[138:139]
	global_load_lds_dwordx4 v[2:3], off
	v_lshlrev_b32_e32 v2, 6, v0
	v_lshlrev_b32_e32 v0, 2, v0
	v_and_or_b32 v1, v2, s74, v1
	v_and_b32_e32 v0, 32, v0
	s_waitcnt vmcnt(10)
	s_barrier
	s_waitcnt vmcnt(6)
	v_bitop3_b32 v2, v1, s7, v0 bitop3:0xde
	v_bitop3_b32 v149, s9, v1, v0 bitop3:0xf6
	s_ashr_i32 s76, s58, 31
	s_ashr_i32 s77, s0, 31
	s_mov_b32 s56, 0
	v_add_u32_e32 v150, 16, v2
	s_barrier
	s_branch .LBB0_120

; #define PG8_STAGE(bufoff, gbase, voff) do { _Pragma("unroll") for (int _i = 0; _i < 2; ++_i) { const char* _gb = (const char*)(gbase) + (size_t)_i * (voff##_q); asm volatile("" : "+s"(_gb)); \
;         __builtin_amdgcn_global_load_lds((const unsigned*)(_gb + (voff)), (LAS unsigned*)(lds + (bufoff) + ldsw + _i * 8192), 16, 0, 0); } } while (0)
; #define PG8_WAIT_V(n) asm volatile("s_waitcnt vmcnt(" #n ")" ::: "memory")
; #define PG8_BAR __builtin_amdgcn_s_barrier()
; template <class Epi, class Sched>
; __device__ __forceinline__ void gemm_phase(int wv, LAS unsigned char* lds, const Gemm g, const Sched& S, const Epi& E) { LIDS
;     ...
;     PG8_STAGE(PG8_SB(0, 0), cB, voffB); PG8_STAGE(PG8_SA(0, 0), cA, voffA); PG8_STAGE(PG8_SB(0, 1), cB + hstepB, voffB); PG8_STAGE(PG8_SA(0, 1), cA + hstepA, voffA);
;     if (wr == 1) PG8_BAR;
;     PG8_WAIT_V(4); PG8_BAR;
;     PG8_STAGE(PG8_SB(1, 0), cB + kstepB, voffB); PG8_STAGE(PG8_SA(1, 0), cA + kstepA, voffA); PG8_STAGE(PG8_SB(1, 1), cB + hstepB + kstepB, voffB);
;     PG8_WAIT_V(6); PG8_BAR;
; PHASE_FN void ph_k(int wv, const Params& p, int layer, LAS unsigned char* lds) { LIDS
;     ...
;     Gemm g{WSP(bf16_t, OFF_PROJ) + C_CKV, WSP(bf16_t, OFF_WK), NIN, 256, 256, (size_t)BM * NIN * 2, (size_t)BM * 256 * 2, 0};
;     StaticOrder S; S.init(SEQ, 1024, G, (bid_l + G / 2) % G); EpiK E{WSP(bf16_t, OFF_KF), WSP(float, OFF_SS)}; gemm_phase(wv, lds, g, S, E);
.LBB0_166:
	v_and_b32_e32 v5, 48, v4
	v_lshlrev_b32_e32 v6, 6, v4
	v_lshlrev_b32_e32 v4, 2, v4
	s_sext_i32_i8 s16, s0
	s_lshl_b32 s0, s5, 13
	v_and_or_b32 v5, v6, s74, v5
	v_and_b32_e32 v4, 32, v4
	v_bitop3_b32 v6, v5, s0, v4 bitop3:0xde
	s_lshl_b32 s0, s4, 5
	s_and_b32 s92, s0, 0x60
	s_lshl_b32 s83, s5, 6
	s_lshl_b32 s0, s92, 7
	s_add_u32 s4, s90, 0x80
	s_addc_u32 s5, s91, 0
	v_mov_b32_e32 v127, v177
	s_add_i32 m0, s58, 0x18000
	v_bitop3_b32 v134, s0, v5, v4 bitop3:0xf6
	v_lshl_add_u64 v[4:5], s[4:5], 0, v[126:127]
	s_add_u32 s4, s90, 0x8080
	s_addc_u32 s5, s91, 0
	global_load_lds_dwordx4 v[4:5], off
	s_add_i32 m0, s58, 0x1a000
	v_lshl_add_u64 v[4:5], s[4:5], 0, v[126:127]
	s_add_u32 s4, s86, 0x80
	s_addc_u32 s5, s87, 0
	v_mov_b32_e32 v125, v177
	global_load_lds_dwordx4 v[4:5], off
	s_add_i32 s0, s58, 0x8000
	v_lshl_add_u64 v[4:5], s[4:5], 0, v[124:125]
	s_add_u32 s4, s86, 0x80080
	s_mov_b32 m0, s0
	s_addc_u32 s5, s87, 0
	global_load_lds_dwordx4 v[4:5], off
	s_add_i32 s59, s58, 0xa000
	v_lshl_add_u64 v[4:5], s[4:5], 0, v[124:125]
	s_add_u32 s4, s90, 0x10080
	s_mov_b32 m0, s59
	s_addc_u32 s5, s91, 0
	global_load_lds_dwordx4 v[4:5], off
	s_add_i32 m0, s58, 0x1c000
	v_mov_b32_e32 v1, v0
	v_lshl_add_u64 v[4:5], s[4:5], 0, v[126:127]
	s_add_u32 s4, s90, 0x18080
	s_addc_u32 s5, s91, 0
	global_load_lds_dwordx4 v[4:5], off
	s_add_i32 m0, s58, 0x1e000
	v_lshl_add_u64 v[4:5], s[4:5], 0, v[126:127]
	global_load_lds_dwordx4 v[4:5], off
	s_waitcnt vmcnt(10)
	s_barrier
	s_waitcnt vmcnt(6)
	s_ashr_i32 s4, s55, 31
	v_writelane_b32 v254, s4, 62
	s_add_i32 s4, s55, s9
	v_mov_b32_e32 v2, v0
	v_mov_b32_e32 v3, v0
	s_sub_i32 s69, s4, s8
	v_add_u32_e32 v135, 16, v6
	s_barrier
	s_branch .LBB0_169

; #define PG8_STAGE(bufoff, gbase, voff) do { _Pragma("unroll") for (int _i = 0; _i < 2; ++_i) { const char* _gb = (const char*)(gbase) + (size_t)_i * (voff##_q); asm volatile("" : "+s"(_gb)); \
;         __builtin_amdgcn_global_load_lds((const unsigned*)(_gb + (voff)), (LAS unsigned*)(lds + (bufoff) + ldsw + _i * 8192), 16, 0, 0); } } while (0)
; #define PG8_WAIT_V(n) asm volatile("s_waitcnt vmcnt(" #n ")" ::: "memory")
; #define PG8_BAR __builtin_amdgcn_s_barrier()
; template <class Epi, class Sched>
; __device__ __forceinline__ void gemm_phase(int wv, LAS unsigned char* lds, const Gemm g, const Sched& S, const Epi& E) { LIDS
;     ...
;     PG8_STAGE(PG8_SB(0, 0), cB, voffB); PG8_STAGE(PG8_SA(0, 0), cA, voffA); PG8_STAGE(PG8_SB(0, 1), cB + hstepB, voffB); PG8_STAGE(PG8_SA(0, 1), cA + hstepA, voffA);
;     if (wr == 1) PG8_BAR;
;     PG8_WAIT_V(4); PG8_BAR;
;     PG8_STAGE(PG8_SB(1, 0), cB + kstepB, voffB); PG8_STAGE(PG8_SA(1, 0), cA + kstepA, voffA); PG8_STAGE(PG8_SB(1, 1), cB + hstepB + kstepB, voffB);
;     PG8_WAIT_V(6); PG8_BAR;
; PHASE_FN void ph_v(int wv, const Params& p, int layer, LAS unsigned char* lds) { LIDS
;     Gemm g{WSP(bf16_t, OFF_WV), WSP(bf16_t, OFF_PROJ) + C_CKV, 256, NIN, 256, (size_t)BM * 256 * 2, (size_t)BM * NIN * 2, 0};
;     StaticOrder S; S.init(1024, SEQ, gdim_l, bid_l); EpiVt E{WSP(bf16_t, OFF_VT), WSP(float, OFF_SS)}; gemm_phase(wv, lds, g, S, E);
.LBB0_184:
	s_lshl_b32 s4, s4, 5
	s_and_b32 s23, s4, 0x60
	s_lshl_b32 s22, s5, 6
	s_lshl_b32 s10, s5, 13
	s_lshl_b32 s11, s23, 7
	s_add_u32 s4, s90, 0x80
	s_addc_u32 s5, s91, 0
	s_add_i32 m0, s18, 0x18000
	v_mov_b32_e32 v141, v177
	v_lshl_add_u64 v[2:3], s[4:5], 0, v[176:177]
	s_add_u32 s4, s90, 0x80080
	s_addc_u32 s5, s91, 0
	global_load_lds_dwordx4 v[2:3], off
	s_add_i32 m0, s18, 0x1a000
	v_lshl_add_u64 v[2:3], s[4:5], 0, v[176:177]
	s_add_u32 s4, s86, 0x80
	s_addc_u32 s5, s87, 0
	global_load_lds_dwordx4 v[2:3], off
	s_add_i32 s24, s18, 0x8000
	v_lshl_add_u64 v[2:3], s[4:5], 0, v[140:141]
	s_add_u32 s4, s86, 0x8080
	s_mov_b32 m0, s24
	s_addc_u32 s5, s87, 0
	global_load_lds_dwordx4 v[2:3], off
	s_add_i32 s25, s18, 0xa000
	v_lshl_add_u64 v[2:3], s[4:5], 0, v[140:141]
	s_add_u32 s4, s90, 0x100080
	s_mov_b32 m0, s25
	s_addc_u32 s5, s91, 0
	global_load_lds_dwordx4 v[2:3], off
	s_add_i32 m0, s18, 0x1c000
	v_and_b32_e32 v5, 48, v4
	v_lshl_add_u64 v[2:3], s[4:5], 0, v[176:177]
	s_add_u32 s4, s90, 0x180080
	s_addc_u32 s5, s91, 0
	global_load_lds_dwordx4 v[2:3], off
	s_add_i32 m0, s18, 0x1e000
	v_lshl_add_u64 v[2:3], s[4:5], 0, v[176:177]
	global_load_lds_dwordx4 v[2:3], off
	v_lshlrev_b32_e32 v6, 6, v4
	v_lshlrev_b32_e32 v4, 2, v4
	v_and_or_b32 v5, v6, s74, v5
	v_and_b32_e32 v4, 32, v4
	s_waitcnt vmcnt(10)
	s_barrier
	s_waitcnt vmcnt(6)
	v_bitop3_b32 v6, v5, s10, v4 bitop3:0xde
	s_sext_i32_i16 s7, s0
	v_mov_b32_e32 v1, v0
	v_mov_b32_e32 v2, v0
	v_mov_b32_e32 v3, v0
	v_bitop3_b32 v156, s11, v5, v4 bitop3:0xf6
	s_ashr_i32 s0, s53, 31
	s_add_i32 s26, s8, s53
	v_add_u32_e32 v157, 16, v6
	s_barrier
	s_branch .LBB0_187

; #define PG8_STAGE(bufoff, gbase, voff) do { _Pragma("unroll") for (int _i = 0; _i < 2; ++_i) { const char* _gb = (const char*)(gbase) + (size_t)_i * (voff##_q); asm volatile("" : "+s"(_gb)); \
;         __builtin_amdgcn_global_load_lds((const unsigned*)(_gb + (voff)), (LAS unsigned*)(lds + (bufoff) + ldsw + _i * 8192), 16, 0, 0); } } while (0)
; #define PG8_WAIT_V(n) asm volatile("s_waitcnt vmcnt(" #n ")" ::: "memory")
; #define PG8_BAR __builtin_amdgcn_s_barrier()
; template <class Epi, class Sched>
; __device__ __forceinline__ void gemm_phase(int wv, LAS unsigned char* lds, const Gemm g, const Sched& S, const Epi& E) { LIDS
;     ...
;     PG8_STAGE(PG8_SB(0, 0), cB, voffB); PG8_STAGE(PG8_SA(0, 0), cA, voffA); PG8_STAGE(PG8_SB(0, 1), cB + hstepB, voffB); PG8_STAGE(PG8_SA(0, 1), cA + hstepA, voffA);
;     if (wr == 1) PG8_BAR;
;     PG8_WAIT_V(4); PG8_BAR;
;     PG8_STAGE(PG8_SB(1, 0), cB + kstepB, voffB); PG8_STAGE(PG8_SA(1, 0), cA + kstepA, voffA); PG8_STAGE(PG8_SB(1, 1), cB + hstepB + kstepB, voffB);
;     PG8_WAIT_V(6); PG8_BAR;
.LBB0_204:
	s_lshl_b32 s6, s6, 5
	s_and_b32 s28, s6, 0x60
	s_lshl_b32 s27, s7, 6
	s_lshl_b32 s8, s7, 13
	s_lshl_b32 s9, s28, 7
	s_add_u32 s6, s86, 0x80
	s_addc_u32 s7, s87, 0
	v_mov_b32_e32 v7, v177
	s_add_i32 m0, s20, 0x18000
	v_mov_b32_e32 v5, v177
	v_lshl_add_u64 v[2:3], s[6:7], 0, v[6:7]
	s_add_u32 s6, s86, 0x8080
	s_addc_u32 s7, s87, 0
	global_load_lds_dwordx4 v[2:3], off
	s_add_i32 m0, s20, 0x1a000
	v_lshl_add_u64 v[2:3], s[6:7], 0, v[6:7]
	s_add_u32 s6, s78, 0x80
	s_addc_u32 s7, s79, 0
	global_load_lds_dwordx4 v[2:3], off
	s_add_i32 s29, s20, 0x8000
	v_lshl_add_u64 v[2:3], s[6:7], 0, v[4:5]
	s_add_u32 s6, s78, 0xc080
	s_mov_b32 m0, s29
	s_addc_u32 s7, s79, 0
	global_load_lds_dwordx4 v[2:3], off
	s_add_i32 s30, s20, 0xa000
	v_lshl_add_u64 v[2:3], s[6:7], 0, v[4:5]
	s_add_u32 s6, s86, 0x10080
	s_mov_b32 m0, s30
	s_addc_u32 s7, s87, 0
	global_load_lds_dwordx4 v[2:3], off
	s_add_i32 s31, s20, 0x1c000
	s_mov_b32 m0, s31
	v_lshl_add_u64 v[2:3], s[6:7], 0, v[6:7]
	s_add_u32 s6, s86, 0x18080
	s_addc_u32 s7, s87, 0
	s_add_i32 s52, s20, 0x1e000
	global_load_lds_dwordx4 v[2:3], off
	s_mov_b32 m0, s52
	v_lshl_add_u64 v[2:3], s[6:7], 0, v[6:7]
	global_load_lds_dwordx4 v[2:3], off
	s_lshr_b32 s6, s0, 31
	v_and_b32_e32 v9, 48, v8
	v_lshlrev_b32_e32 v10, 6, v8
	v_lshlrev_b32_e32 v8, 2, v8
	s_add_i32 s6, s0, s6
	v_and_or_b32 v9, v10, s74, v9
	v_and_b32_e32 v8, 32, v8
	s_ashr_i32 s6, s6, 1
	v_bitop3_b32 v10, v9, s8, v8 bitop3:0xde
	s_add_i32 s8, s6, s10
	s_cmpk_lt_i32 s10, 0x80
	s_cselect_b64 s[6:7], -1, 0
	s_abs_i32 s11, s0
	v_bitop3_b32 v8, s9, v9, v8 bitop3:0xf6
	v_cvt_f32_u32_e32 v9, s11
	s_add_i32 s9, s10, 0xffffff80
	s_lshl_b32 s10, s10, 5
	s_lshr_b32 s9, s9, 2
	v_rcp_iflag_f32_e32 v9, v9
	s_and_b32 s10, s10, 0xe0
	s_add_i32 s9, s9, s10
	s_sub_i32 s10, 0, s11
	v_mul_f32_e32 v9, 0x4f7ffffe, v9
	v_cvt_u32_f32_e32 v9, v9
	s_or_b32 s53, s9, 1
	s_ashr_i32 s9, s8, 31
	s_abs_i32 s8, s8
	v_readfirstlane_b32 s12, v9
	s_mul_i32 s10, s10, s12
	s_mul_hi_u32 s10, s12, s10
	s_add_i32 s12, s12, s10
	s_mul_hi_u32 s10, s8, s12
	s_mul_i32 s10, s10, s11
	s_sub_i32 s8, s8, s10
	s_sub_i32 s10, s8, s11
	s_cmp_ge_u32 s8, s11
	s_cselect_b32 s8, s10, s8
	s_sub_i32 s10, s8, s11
	s_cmp_ge_u32 s8, s11
	s_cselect_b32 s8, s10, s8
	s_waitcnt vmcnt(10)
	s_barrier
	s_waitcnt vmcnt(6)
	s_xor_b32 s8, s8, s9
	s_add_i32 s8, s0, s8
	v_mov_b32_e32 v1, v0
	v_mov_b32_e32 v2, v0
	v_mov_b32_e32 v3, v0
	s_mov_b32 s55, 0
	s_sub_i32 s56, s8, s9
	s_xor_b64 s[6:7], s[6:7], -1
	v_add_u32_e32 v9, 16, v10
	s_barrier
	s_branch .LBB0_206

; #define PG8_STAGE(bufoff, gbase, voff) do { _Pragma("unroll") for (int _i = 0; _i < 2; ++_i) { const char* _gb = (const char*)(gbase) + (size_t)_i * (voff##_q); asm volatile("" : "+s"(_gb)); \
;         __builtin_amdgcn_global_load_lds((const unsigned*)(_gb + (voff)), (LAS unsigned*)(lds + (bufoff) + ldsw + _i * 8192), 16, 0, 0); } } while (0)
; #define PG8_WAIT_V(n) asm volatile("s_waitcnt vmcnt(" #n ")" ::: "memory")
; #define PG8_BAR __builtin_amdgcn_s_barrier()
; template <class Epi, class Sched>
; __device__ __forceinline__ void gemm_phase(int wv, LAS unsigned char* lds, const Gemm g, const Sched& S, const Epi& E) { LIDS
;     ...
;     PG8_STAGE(PG8_SB(0, 0), cB, voffB); PG8_STAGE(PG8_SA(0, 0), cA, voffA); PG8_STAGE(PG8_SB(0, 1), cB + hstepB, voffB); PG8_STAGE(PG8_SA(0, 1), cA + hstepA, voffA);
;     if (wr == 1) PG8_BAR;
;     PG8_WAIT_V(4); PG8_BAR;
;     PG8_STAGE(PG8_SB(1, 0), cB + kstepB, voffB); PG8_STAGE(PG8_SA(1, 0), cA + kstepA, voffA); PG8_STAGE(PG8_SB(1, 1), cB + hstepB + kstepB, voffB);
;     PG8_WAIT_V(6); PG8_BAR;
.LBB0_335:
	s_and_b32 s53, s4, 3
	s_lshl_b32 s76, s0, 6
	s_lshl_b32 s0, s0, 13
	s_lshl_b32 s77, s53, 5
	s_lshl_b32 s7, s53, 12
	s_add_u32 s4, s10, 0x80
	s_addc_u32 s5, s11, 0
	v_mov_b32_e32 v135, v177
	s_add_i32 m0, s59, 0x18000
	v_mov_b32_e32 v133, v177
	v_lshl_add_u64 v[2:3], s[4:5], 0, v[134:135]
	s_add_u32 s4, s10, 0x40080
	s_addc_u32 s5, s11, 0
	global_load_lds_dwordx4 v[2:3], off
	s_add_i32 m0, s59, 0x1a000
	v_lshl_add_u64 v[2:3], s[4:5], 0, v[134:135]
	s_add_u32 s4, s8, 0x80
	s_addc_u32 s5, s9, 0
	global_load_lds_dwordx4 v[2:3], off
	s_add_i32 s82, s59, 0x8000
	v_lshl_add_u64 v[2:3], s[4:5], 0, v[132:133]
	s_add_u32 s4, s8, 0x40080
	s_mov_b32 m0, s82
	s_addc_u32 s5, s9, 0
	global_load_lds_dwordx4 v[2:3], off
	s_add_i32 s83, s59, 0xa000
	v_lshl_add_u64 v[2:3], s[4:5], 0, v[132:133]
	s_add_u32 s4, s10, 0x80080
	s_mov_b32 m0, s83
	s_addc_u32 s5, s11, 0
	global_load_lds_dwordx4 v[2:3], off
	s_add_i32 m0, s59, 0x1c000
	v_and_b32_e32 v1, 48, v0
	v_lshl_add_u64 v[2:3], s[4:5], 0, v[134:135]
	s_add_u32 s4, s10, 0xc0080
	s_addc_u32 s5, s11, 0
	global_load_lds_dwordx4 v[2:3], off
	s_add_i32 m0, s59, 0x1e000
	v_lshl_add_u64 v[2:3], s[4:5], 0, v[134:135]
	global_load_lds_dwordx4 v[2:3], off
	v_lshlrev_b32_e32 v2, 6, v0
	v_lshlrev_b32_e32 v0, 2, v0
	v_and_or_b32 v1, v2, s74, v1
	v_and_b32_e32 v0, 32, v0
	s_waitcnt vmcnt(10)
	s_barrier
	s_waitcnt vmcnt(6)
	v_bitop3_b32 v2, v1, s0, v0 bitop3:0xde
	v_readlane_b32 s26, v253, 22
	v_bitop3_b32 v145, s7, v1, v0 bitop3:0xf6
	s_ashr_i32 s70, s56, 31
	s_ashr_i32 s52, s55, 31
	s_mov_b32 s16, 0
	v_add_u32_e32 v146, 16, v2
	v_readlane_b32 s27, v253, 23
	s_barrier
	s_branch .LBB0_338
